# dilated attention unit: nt hint on the once-consumed OB output stores
# baseline (speedup 1.0000x reference)
.LBB0_397:
	v_mov_b32_e32 v2, v183
	s_nop 1
	v_permlane32_swap_b32_e32 v183, v2
	v_add_f32_e32 v2, v183, v2
	v_div_scale_f32 v3, s[0:1], v2, v2, 1.0
	v_rcp_f32_e32 v4, v3
	s_lshl_b32 s0, s92, 13
	s_add_i32 s0, s0, 0
	v_lshlrev_b32_e32 v0, 3, v156
	v_fma_f32 v5, -v3, v4, 1.0
	v_fmac_f32_e32 v4, v5, v4
	v_div_scale_f32 v5, vcc, 1.0, v2, 1.0
	v_mul_f32_e32 v6, v5, v4
	v_fma_f32 v7, -v3, v6, v5
	v_fmac_f32_e32 v6, v7, v4
	v_fma_f32 v3, -v3, v6, v5
	s_add_i32 s0, s0, 0x10000
	v_div_fmas_f32 v3, v3, v4, v6
	v_div_fixup_f32 v4, v3, v2, 1.0
	v_add3_u32 v0, s0, v81, v0
	v_lshlrev_b32_e32 v3, 4, v157
	v_add_u32_e32 v5, v0, v3
	v_pk_mul_f32 v[6:7], v[64:65], v[4:5] op_sel_hi:[1,0]
	v_pk_mul_f32 v[8:9], v[66:67], v[4:5] op_sel_hi:[1,0]
	v_cvt_pk_bf16_f32 v6, v6, v7
	v_cvt_pk_bf16_f32 v7, v8, v9
	s_waitcnt vmcnt(0)
	ds_write_b64 v5, v[6:7]
	v_xad_u32 v5, v3, 16, v0
	v_pk_mul_f32 v[6:7], v[68:69], v[4:5] op_sel_hi:[1,0]
	v_pk_mul_f32 v[8:9], v[70:71], v[4:5] op_sel_hi:[1,0]
	v_cvt_pk_bf16_f32 v6, v6, v7
	v_cvt_pk_bf16_f32 v7, v8, v9
	ds_write_b64 v5, v[6:7]
	v_xad_u32 v5, v3, 32, v0
	v_pk_mul_f32 v[6:7], v[72:73], v[4:5] op_sel_hi:[1,0]
	v_pk_mul_f32 v[8:9], v[74:75], v[4:5] op_sel_hi:[1,0]
	v_cvt_pk_bf16_f32 v6, v6, v7
	v_cvt_pk_bf16_f32 v7, v8, v9
	ds_write_b64 v5, v[6:7]
	v_xad_u32 v5, v3, 48, v0
	v_pk_mul_f32 v[6:7], v[76:77], v[4:5] op_sel_hi:[1,0]
	v_pk_mul_f32 v[8:9], v[78:79], v[4:5] op_sel_hi:[1,0]
	v_cvt_pk_bf16_f32 v6, v6, v7
	v_cvt_pk_bf16_f32 v7, v8, v9
	ds_write_b64 v5, v[6:7]
	v_xad_u32 v5, v3, 64, v0
	v_pk_mul_f32 v[6:7], v[48:49], v[4:5] op_sel_hi:[1,0]
	v_pk_mul_f32 v[8:9], v[50:51], v[4:5] op_sel_hi:[1,0]
	v_cvt_pk_bf16_f32 v6, v6, v7
	v_cvt_pk_bf16_f32 v7, v8, v9
	ds_write_b64 v5, v[6:7]
	v_xad_u32 v5, v3, s69, v0
	v_pk_mul_f32 v[6:7], v[52:53], v[4:5] op_sel_hi:[1,0]
	v_pk_mul_f32 v[8:9], v[54:55], v[4:5] op_sel_hi:[1,0]
	v_cvt_pk_bf16_f32 v6, v6, v7
	v_cvt_pk_bf16_f32 v7, v8, v9
	ds_write_b64 v5, v[6:7]
	v_xad_u32 v5, v3, s70, v0
	v_pk_mul_f32 v[6:7], v[56:57], v[4:5] op_sel_hi:[1,0]
	v_pk_mul_f32 v[8:9], v[58:59], v[4:5] op_sel_hi:[1,0]
	v_cvt_pk_bf16_f32 v6, v6, v7
	v_cvt_pk_bf16_f32 v7, v8, v9
	ds_write_b64 v5, v[6:7]
	v_xad_u32 v5, v3, s71, v0
	v_pk_mul_f32 v[6:7], v[60:61], v[4:5] op_sel_hi:[1,0]
	v_pk_mul_f32 v[8:9], v[62:63], v[4:5] op_sel_hi:[1,0]
	v_cvt_pk_bf16_f32 v6, v6, v7
	v_cvt_pk_bf16_f32 v7, v8, v9
	ds_write_b64 v5, v[6:7]
	v_xad_u32 v5, v3, s72, v0
	v_pk_mul_f32 v[6:7], v[32:33], v[4:5] op_sel_hi:[1,0]
	v_pk_mul_f32 v[8:9], v[34:35], v[4:5] op_sel_hi:[1,0]
	v_cvt_pk_bf16_f32 v6, v6, v7
	v_cvt_pk_bf16_f32 v7, v8, v9
	ds_write_b64 v5, v[6:7]
	v_xad_u32 v5, v3, s73, v0
	v_pk_mul_f32 v[6:7], v[36:37], v[4:5] op_sel_hi:[1,0]
	v_pk_mul_f32 v[8:9], v[38:39], v[4:5] op_sel_hi:[1,0]
	v_cvt_pk_bf16_f32 v6, v6, v7
	v_cvt_pk_bf16_f32 v7, v8, v9
	ds_write_b64 v5, v[6:7]
	v_xad_u32 v5, v3, s79, v0
	v_pk_mul_f32 v[6:7], v[40:41], v[4:5] op_sel_hi:[1,0]
	v_pk_mul_f32 v[8:9], v[42:43], v[4:5] op_sel_hi:[1,0]
	v_cvt_pk_bf16_f32 v6, v6, v7
	v_cvt_pk_bf16_f32 v7, v8, v9
	ds_write_b64 v5, v[6:7]
	v_xad_u32 v5, v3, s80, v0
	v_pk_mul_f32 v[6:7], v[44:45], v[4:5] op_sel_hi:[1,0]
	v_pk_mul_f32 v[8:9], v[46:47], v[4:5] op_sel_hi:[1,0]
	v_cvt_pk_bf16_f32 v6, v6, v7
	v_cvt_pk_bf16_f32 v7, v8, v9
	ds_write_b64 v5, v[6:7]
	v_xad_u32 v5, v3, s81, v0
	v_pk_mul_f32 v[6:7], v[16:17], v[4:5] op_sel_hi:[1,0]
	v_pk_mul_f32 v[8:9], v[18:19], v[4:5] op_sel_hi:[1,0]
	v_cvt_pk_bf16_f32 v6, v6, v7
	v_cvt_pk_bf16_f32 v7, v8, v9
	ds_write_b64 v5, v[6:7]
	v_xad_u32 v5, v3, s82, v0
	v_pk_mul_f32 v[6:7], v[20:21], v[4:5] op_sel_hi:[1,0]
	v_pk_mul_f32 v[8:9], v[22:23], v[4:5] op_sel_hi:[1,0]
	v_cvt_pk_bf16_f32 v6, v6, v7
	v_cvt_pk_bf16_f32 v7, v8, v9
	ds_write_b64 v5, v[6:7]
	v_xad_u32 v5, v3, s83, v0
	v_pk_mul_f32 v[6:7], v[24:25], v[4:5] op_sel_hi:[1,0]
	v_pk_mul_f32 v[8:9], v[26:27], v[4:5] op_sel_hi:[1,0]
	v_cvt_pk_bf16_f32 v6, v6, v7
	v_cvt_pk_bf16_f32 v7, v8, v9
	ds_write_b64 v5, v[6:7]
	v_pk_mul_f32 v[6:7], v[28:29], v[4:5] op_sel_hi:[1,0]
	v_pk_mul_f32 v[4:5], v[30:31], v[4:5] op_sel_hi:[1,0]
	v_xad_u32 v0, v3, s84, v0
	v_cvt_pk_bf16_f32 v6, v6, v7
	v_cvt_pk_bf16_f32 v7, v4, v5
	ds_write_b64 v0, v[6:7]
	v_lshlrev_b32_e32 v0, 4, v152
	v_and_b32_e32 v0, 0xf0, v0
	v_add_u32_e32 v3, s0, v0
	v_add_u32_e32 v0, v80, v153
	v_ashrrev_i32_e32 v4, s60, v0
	v_lshlrev_b32_e32 v0, s59, v0
	v_and_b32_e32 v0, 0x7ff, v0
	s_lshl_b32 s0, s61, 14
	v_add_u32_e32 v8, v0, v4
	s_waitcnt lgkmcnt(0)
	s_or_b32 s20, s91, s0
	v_ashrrev_i32_e32 v9, 31, v8
	v_lshl_add_u32 v0, v153, 8, v3
	ds_read_b128 v[4:7], v0
	v_lshl_add_u64 v[8:9], v[8:9], 0, s[20:21]
	v_lshlrev_b64 v[8:9], 10, v[8:9]
	v_xor_b32_e32 v0, v153, v152
	v_lshl_add_u64 v[8:9], s[46:47], 0, v[8:9]
	s_lshl_b32 s0, s90, 1
	s_mov_b32 s1, s21
	v_lshlrev_b32_e32 v0, 4, v0
	v_lshl_add_u64 v[8:9], v[8:9], 0, s[0:1]
	v_and_b32_e32 v0, 0xf0, v0
	v_lshl_add_u64 v[12:13], v[8:9], 0, v[0:1]
	v_or_b32_e32 v14, 4, v153
	s_waitcnt lgkmcnt(0)
	global_store_dwordx4 v[12:13], v[4:7], off nt
	v_lshl_add_u32 v8, v14, 8, v3
	ds_read_b128 v[8:11], v8
	v_add_u32_e32 v4, v80, v14
	v_ashrrev_i32_e32 v5, s60, v4
	v_lshlrev_b32_e32 v4, s59, v4
	v_and_b32_e32 v4, 0x7ff, v4
	v_add_u32_e32 v4, v4, v5
	v_ashrrev_i32_e32 v5, 31, v4
	v_lshl_add_u64 v[4:5], v[4:5], 0, s[20:21]
	v_lshlrev_b64 v[4:5], 10, v[4:5]
	v_bitop3_b32 v6, v153, v152, 4 bitop3:0x36
	v_lshl_add_u64 v[4:5], s[46:47], 0, v[4:5]
	v_lshlrev_b32_e32 v6, 4, v6
	v_lshl_add_u64 v[4:5], v[4:5], 0, s[0:1]
	v_and_b32_e32 v6, 0xf0, v6
	v_mov_b32_e32 v7, v1
	v_lshl_add_u64 v[4:5], v[4:5], 0, v[6:7]
	s_waitcnt lgkmcnt(0)
	global_store_dwordx4 v[4:5], v[8:11], off nt
	v_or_b32_e32 v4, 8, v153
	v_add_u32_e32 v5, v80, v4
	v_ashrrev_i32_e32 v6, s60, v5
	v_lshlrev_b32_e32 v5, s59, v5
	v_and_b32_e32 v5, 0x7ff, v5
	v_add_u32_e32 v8, v5, v6
	v_ashrrev_i32_e32 v9, 31, v8
	v_lshl_add_u32 v4, v4, 8, v3
	ds_read_b128 v[4:7], v4
	v_lshl_add_u64 v[8:9], v[8:9], 0, s[20:21]
	v_lshlrev_b64 v[8:9], 10, v[8:9]
	v_bitop3_b32 v10, v153, v152, 8 bitop3:0x36
	v_lshl_add_u64 v[8:9], s[46:47], 0, v[8:9]
	v_lshlrev_b32_e32 v10, 4, v10
	v_lshl_add_u64 v[8:9], v[8:9], 0, s[0:1]
	v_and_b32_e32 v10, 0xf0, v10
	v_mov_b32_e32 v11, v1
	v_or_b32_e32 v14, 12, v153
	v_lshl_add_u64 v[12:13], v[8:9], 0, v[10:11]
	v_lshl_add_u32 v8, v14, 8, v3
	ds_read_b128 v[8:11], v8
	s_waitcnt lgkmcnt(0)
	global_store_dwordx4 v[12:13], v[4:7], off nt
	v_cmp_gt_u32_e32 vcc, 32, v152
	s_nop 0
	v_add_u32_e32 v4, v80, v14
	v_ashrrev_i32_e32 v5, s60, v4
	v_lshlrev_b32_e32 v4, s59, v4
	v_and_b32_e32 v4, 0x7ff, v4
	v_add_u32_e32 v4, v4, v5
	v_ashrrev_i32_e32 v5, 31, v4
	v_lshl_add_u64 v[4:5], v[4:5], 0, s[20:21]
	v_lshlrev_b64 v[4:5], 10, v[4:5]
	v_bitop3_b32 v6, v153, v152, 12 bitop3:0x36
	v_lshl_add_u64 v[4:5], s[46:47], 0, v[4:5]
	v_lshlrev_b32_e32 v6, 4, v6
	v_lshl_add_u64 v[4:5], v[4:5], 0, s[0:1]
	v_and_b32_e32 v6, 0xf0, v6
	v_mov_b32_e32 v7, v1
	v_lshl_add_u64 v[4:5], v[4:5], 0, v[6:7]
	global_store_dwordx4 v[4:5], v[8:11], off nt
	v_or_b32_e32 v4, 16, v153
	v_add_u32_e32 v5, v80, v4
	v_ashrrev_i32_e32 v6, s60, v5
	v_lshlrev_b32_e32 v5, s59, v5
	v_and_b32_e32 v5, 0x7ff, v5
	v_add_u32_e32 v8, v5, v6
	v_ashrrev_i32_e32 v9, 31, v8
	v_lshl_add_u32 v4, v4, 8, v3
	v_lshl_add_u64 v[8:9], v[8:9], 0, s[20:21]
	ds_read_b128 v[4:7], v4
	v_lshlrev_b64 v[8:9], 10, v[8:9]
	v_lshl_add_u64 v[8:9], s[46:47], 0, v[8:9]
	v_lshl_add_u64 v[8:9], v[8:9], 0, s[0:1]
	v_lshl_add_u64 v[12:13], v[8:9], 0, v[0:1]
	v_or_b32_e32 v0, 20, v153
	v_lshl_add_u32 v8, v0, 8, v3
	v_add_u32_e32 v0, v80, v0
	ds_read_b128 v[8:11], v8
	s_waitcnt lgkmcnt(0)
	global_store_dwordx4 v[12:13], v[4:7], off nt
	s_nop 1
	v_ashrrev_i32_e32 v4, s60, v0
	v_lshlrev_b32_e32 v0, s59, v0
	v_and_b32_e32 v0, 0x7ff, v0
	v_add_u32_e32 v4, v0, v4
	v_ashrrev_i32_e32 v5, 31, v4
	v_lshl_add_u64 v[4:5], v[4:5], 0, s[20:21]
	v_lshlrev_b64 v[4:5], 10, v[4:5]
	v_bitop3_b32 v0, v153, v152, 20 bitop3:0x36
	v_lshl_add_u64 v[4:5], s[46:47], 0, v[4:5]
	v_lshlrev_b32_e32 v0, 4, v0
	v_lshl_add_u64 v[4:5], v[4:5], 0, s[0:1]
	v_and_b32_e32 v0, 0xf0, v0
	v_lshl_add_u64 v[4:5], v[4:5], 0, v[0:1]
	v_or_b32_e32 v0, 24, v153
	global_store_dwordx4 v[4:5], v[8:11], off nt
	v_add_u32_e32 v4, v80, v0
	v_ashrrev_i32_e32 v5, s60, v4
	v_lshlrev_b32_e32 v4, s59, v4
	v_and_b32_e32 v4, 0x7ff, v4
	v_add_u32_e32 v8, v4, v5
	v_ashrrev_i32_e32 v9, 31, v8
	v_lshl_add_u32 v0, v0, 8, v3
	v_lshl_add_u64 v[8:9], v[8:9], 0, s[20:21]
	ds_read_b128 v[4:7], v0
	v_lshlrev_b64 v[8:9], 10, v[8:9]
	v_bitop3_b32 v0, v153, v152, 24 bitop3:0x36
	v_lshl_add_u64 v[8:9], s[46:47], 0, v[8:9]
	v_lshlrev_b32_e32 v0, 4, v0
	v_lshl_add_u64 v[8:9], v[8:9], 0, s[0:1]
	v_and_b32_e32 v0, 0xf0, v0
	v_lshl_add_u64 v[12:13], v[8:9], 0, v[0:1]
	v_or_b32_e32 v0, 28, v153
	v_lshl_add_u32 v3, v0, 8, v3
	v_add_u32_e32 v0, v80, v0
	ds_read_b128 v[8:11], v3
	v_ashrrev_i32_e32 v3, s60, v0
	v_lshlrev_b32_e32 v0, s59, v0
	v_and_b32_e32 v0, 0x7ff, v0
	s_waitcnt lgkmcnt(0)
	global_store_dwordx4 v[12:13], v[4:7], off nt
	s_nop 1
	v_add_u32_e32 v4, v0, v3
	v_ashrrev_i32_e32 v5, 31, v4
	v_lshl_add_u64 v[4:5], v[4:5], 0, s[20:21]
	v_lshlrev_b64 v[4:5], 10, v[4:5]
	v_bitop3_b32 v0, v153, v152, 28 bitop3:0x36
	v_lshl_add_u64 v[4:5], s[46:47], 0, v[4:5]
	v_lshlrev_b32_e32 v0, 4, v0
	v_lshl_add_u64 v[4:5], v[4:5], 0, s[0:1]
	v_and_b32_e32 v0, 0xf0, v0
	v_lshl_add_u64 v[4:5], v[4:5], 0, v[0:1]
	global_store_dwordx4 v[4:5], v[8:11], off nt
	s_and_saveexec_b64 s[0:1], vcc
	s_cbranch_execz .LBB0_399
	v_lshlrev_b32_e32 v0, s59, v155
	v_and_b32_e32 v0, 0x7ff, v0
	v_log_f32_e32 v4, v2
	v_add_u32_e32 v2, v0, v154
	v_ashrrev_i32_e32 v3, 31, v2
	v_lshl_add_u64 v[2:3], v[2:3], 0, s[20:21]
	v_lshl_add_u64 v[2:3], v[2:3], 4, s[12:13]
	s_lshl_b32 s20, s58, 2
	v_add_f32_e32 v0, v96, v4
	v_lshl_add_u64 v[2:3], v[2:3], 0, s[20:21]
	global_store_dword v[2:3], v0, off
